# up-GEMM tile order: each XCD owns whole 8-row groups, column tiles rotated by 4 per XCD
# speedup vs baseline: 1.0051x; 1.0036x over previous
.LBB0_330:
	s_cmpk_lt_i32 s86, 0x28a
	s_cselect_b64 s[4:5], -1, 0
	v_writelane_b32 v252, s4, 6
	s_ashr_i32 s87, s86, 31
	s_ashr_i32 s89, s85, 31
	v_writelane_b32 v252, s5, 7
	s_lshr_b32 s4, s87, 29
	s_add_i32 s5, s86, s4
	s_ashr_i32 s4, s5, 3
	s_and_b32 s5, s5, -8
	s_sub_i32 s5, s86, s5
	s_mul_i32 s6, s5, 0x51
	s_add_i32 s6, s6, 2
	s_add_u32 s96, s0, 0x4200
	s_addc_u32 s97, s1, 0
	s_add_u32 s8, s0, 0x4400
	s_addc_u32 s9, s1, 0
	v_writelane_b32 v252, s8, 8
	s_mul_hi_i32 s77, s94, 0x2800
	v_writelane_b32 v255, s88, 0
	v_writelane_b32 v252, s9, 9
	s_add_u32 s8, s0, 0x4500
	s_addc_u32 s9, s1, 0
	v_writelane_b32 v252, s8, 10
	s_mul_i32 s76, s94, 0x2800
	s_mov_b32 s29, 0
	v_writelane_b32 v252, s9, 11
	s_add_u32 s8, s0, 0x4600
	s_addc_u32 s9, s1, 0
	v_writelane_b32 v252, s8, 12
	v_mov_b32_e32 v96, 0
	v_mov_b32_e32 v176, 0x3ecc95a3
	v_writelane_b32 v252, s9, 13
	s_add_u32 s8, s0, 0x4700
	s_addc_u32 s9, s1, 0
	v_writelane_b32 v252, s8, 14
	v_mov_b32_e32 v177, 0x358637bd
	v_mov_b32_e32 v234, 0x260
	v_writelane_b32 v252, s9, 15
	s_add_u32 s8, s0, 0x4800
	s_addc_u32 s9, s1, 0
	v_writelane_b32 v252, s8, 16
	v_mov_b32_e32 v178, 0x40135761
	v_mov_b32_e32 v179, 0x7f800000
	v_writelane_b32 v252, s9, 17
	s_add_u32 s8, s0, 0x4900
	s_addc_u32 s9, s1, 0
	v_writelane_b32 v252, s8, 18
	v_mov_b32_e32 v146, 0x3f317218
	v_mov_b32_e32 v181, 0xff800000
	v_writelane_b32 v252, s9, 19
	s_add_u32 s8, s0, 0x4a00
	s_addc_u32 s9, s1, 0
	v_writelane_b32 v252, s8, 20
	v_mov_b32_e32 v183, 0x400
	v_mov_b32_e32 v182, 0x800
	v_writelane_b32 v252, s9, 21
	s_add_u32 s8, s0, 0x4b00
	s_addc_u32 s9, s1, 0
	v_writelane_b32 v252, s8, 22
	v_mov_b32_e32 v184, 0xc00
	s_mov_b32 s78, 0x10000
	v_writelane_b32 v252, s9, 23
	s_add_u32 s8, s0, 0x4c00
	s_addc_u32 s9, s1, 0
	v_writelane_b32 v252, s8, 24
	s_movk_i32 s79, 0x1000
	s_movk_i32 s40, 0x7f
	v_writelane_b32 v252, s9, 25
	s_add_u32 s8, s0, 0x4d00
	s_addc_u32 s9, s1, 0
	v_writelane_b32 v252, s8, 26
	s_movk_i32 s42, 0x2800
	s_mov_b32 s43, 0xbfb8aa3b
	v_writelane_b32 v252, s9, 27
	s_add_u32 s8, s0, 0x4e00
	s_addc_u32 s9, s1, 0
	v_writelane_b32 v252, s8, 28
	s_mov_b32 s34, 0x42ce8ed0
	s_mov_b32 s35, 0xc2b17218
	v_writelane_b32 v252, s9, 29
	s_add_u32 s8, s0, 0x4f00
	s_addc_u32 s9, s1, 0
	v_writelane_b32 v252, s8, 30
	s_movk_i32 s36, 0x7fff
	s_mov_b32 s68, 0xffff0000
	v_writelane_b32 v252, s9, 31
	s_add_u32 s8, s0, 0x5000
	s_addc_u32 s9, s1, 0
	v_writelane_b32 v252, s8, 32
	s_movk_i32 s69, 0x810
	s_mov_b32 s22, 0xff800000
	v_writelane_b32 v252, s9, 33
	s_add_u32 s8, s0, 0x5100
	s_addc_u32 s9, s1, 0
	v_writelane_b32 v252, s8, 34
	s_movk_i32 s70, 0x81
	s_mov_b32 s23, 0x1da6f000
	v_writelane_b32 v252, s9, 35
	s_add_u32 s8, s0, 0x5200
	s_addc_u32 s9, s1, 0
	v_writelane_b32 v252, s8, 36
	s_movk_i32 s30, 0xffdf
	s_mov_b32 s26, 0x41000000
	v_writelane_b32 v252, s9, 37
	s_add_u32 s8, s0, 0x5300
	s_addc_u32 s9, s1, 0
	v_writelane_b32 v252, s8, 38
	s_cmp_eq_u32 s33, 15
	s_mov_b32 s53, 0xf800000
	v_writelane_b32 v252, s9, 39
	s_cselect_b64 s[8:9], -1, 0
	v_writelane_b32 v252, s8, 40
	s_cmp_eq_u32 s33, 14
	s_mov_b64 s[58:59], 0x80
	v_writelane_b32 v252, s9, 41
	s_cselect_b64 s[8:9], -1, 0
	v_writelane_b32 v252, s8, 42
	s_cmp_eq_u32 s33, 13
	s_nop 0
	v_writelane_b32 v252, s9, 43
	s_cselect_b64 s[8:9], -1, 0
	v_writelane_b32 v252, s8, 44
	s_cmp_eq_u32 s33, 12
	s_nop 0
	v_writelane_b32 v252, s9, 45
	s_cselect_b64 s[8:9], -1, 0
	v_writelane_b32 v252, s8, 46
	s_cmp_eq_u32 s33, 11
	s_nop 0
	v_writelane_b32 v252, s9, 47
	s_cselect_b64 s[8:9], -1, 0
	v_writelane_b32 v252, s8, 48
	s_cmp_eq_u32 s33, 10
	s_nop 0
	v_writelane_b32 v252, s9, 49
	s_cselect_b64 s[8:9], -1, 0
	v_writelane_b32 v252, s8, 50
	s_cmp_eq_u32 s33, 9
	s_nop 0
	v_writelane_b32 v252, s9, 51
	s_cselect_b64 s[8:9], -1, 0
	v_writelane_b32 v252, s8, 52
	s_cmp_eq_u32 s33, 8
	s_nop 0
	v_writelane_b32 v252, s9, 53
	s_cselect_b64 s[8:9], -1, 0
	v_writelane_b32 v252, s8, 54
	s_cmp_eq_u32 s33, 7
	s_nop 0
	v_writelane_b32 v252, s9, 55
	s_cselect_b64 s[8:9], -1, 0
	v_writelane_b32 v252, s8, 56
	s_cmp_eq_u32 s33, 6
	s_nop 0
	v_writelane_b32 v252, s9, 57
	s_cselect_b64 s[8:9], -1, 0
	v_writelane_b32 v252, s8, 58
	s_cmp_eq_u32 s33, 5
	s_nop 0
	v_writelane_b32 v252, s9, 59
	s_cselect_b64 s[8:9], -1, 0
	v_writelane_b32 v252, s8, 60
	s_cmp_eq_u32 s33, 4
	s_nop 0
	v_writelane_b32 v252, s9, 61
	s_cselect_b64 s[8:9], -1, 0
	v_writelane_b32 v252, s8, 62
	s_cmp_eq_u32 s33, 3
	s_nop 0
	v_writelane_b32 v252, s9, 63
	s_cselect_b64 s[8:9], -1, 0
	v_writelane_b32 v253, s8, 0
	s_cmp_eq_u32 s33, 2
	s_nop 0
	v_writelane_b32 v253, s9, 1
	s_cselect_b64 s[8:9], -1, 0
	v_writelane_b32 v253, s8, 2
	s_cmp_eq_u32 s33, 1
	s_nop 0
	v_writelane_b32 v253, s9, 3
	s_cselect_b64 s[8:9], -1, 0
	v_writelane_b32 v253, s8, 4
	s_cmp_eq_u32 s33, 0
	s_nop 0
	v_writelane_b32 v253, s9, 5
	s_cselect_b64 s[8:9], -1, 0
	s_lshl_b32 s7, s33, 8
	s_add_u32 s2, s2, s7
	v_writelane_b32 v253, s8, 6
	s_addc_u32 s3, s3, 0
	s_nop 0
	v_writelane_b32 v253, s9, 7
	s_add_u32 s8, s2, 0x1400
	s_addc_u32 s9, s3, 0
	v_writelane_b32 v253, s8, 8
	s_add_u32 s2, s2, 0x2400
	s_addc_u32 s3, s3, 0
	v_writelane_b32 v253, s9, 9
	v_writelane_b32 v253, s2, 10
	v_readlane_b32 s9, v252, 5
	s_nop 0
	v_writelane_b32 v253, s3, 11
	s_add_u32 s2, s0, 0x7400
	s_addc_u32 s3, s1, 0
	v_writelane_b32 v253, s2, 12
	s_add_u32 s0, s0, 0x7500
	s_addc_u32 s1, s1, 0
	v_writelane_b32 v253, s3, 13
	v_writelane_b32 v253, s0, 14
	s_cmpk_gt_i32 s86, 0xff
	s_nop 0
	v_writelane_b32 v253, s1, 15
	s_cselect_b64 s[0:1], -1, 0
	v_writelane_b32 v253, s0, 16
	s_cmpk_lt_u32 s48, 0x100
	s_nop 0
	v_writelane_b32 v253, s1, 17
	s_cselect_b64 s[0:1], -1, 0
	v_writelane_b32 v253, s0, 18
	s_nop 1
	v_writelane_b32 v253, s1, 19
	s_bfe_u32 s0, s48, 0x20006
	s_lshl_b32 s1, s88, 7
	s_lshl_b32 s80, s0, 5
	s_cmp_eq_u32 s0, 0
	s_cselect_b64 s[82:83], -1, 0
	s_cmp_lg_u32 s0, 0
	v_writelane_b32 v253, s1, 20
	s_cselect_b64 s[2:3], -1, 0
	v_writelane_b32 v253, s2, 21
	s_cmp_gt_u32 s0, 1
	s_nop 0
	v_writelane_b32 v253, s3, 22
	s_cselect_b64 s[2:3], -1, 0
	v_writelane_b32 v253, s2, 23
	s_cmp_eq_u32 s0, 3
	s_nop 0
	v_writelane_b32 v253, s3, 24
	s_cselect_b64 s[2:3], -1, 0
	s_lshr_b32 s81, s48, 8
	s_lshl_b32 s1, s81, 14
	s_add_i32 s84, 0, 0x10000
	v_writelane_b32 v253, s2, 25
	s_add_i32 s1, s84, s1
	s_cmp_eq_u32 s0, 1
	v_writelane_b32 v253, s3, 26
	v_writelane_b32 v253, s1, 27
	s_cselect_b64 s[2:3], -1, 0
	v_writelane_b32 v253, s2, 28
	s_cmp_eq_u32 s0, 2
	s_cselect_b64 s[0:1], -1, 0
	v_writelane_b32 v253, s3, 29
	v_writelane_b32 v253, s0, 30
	s_lshl_b32 s15, s88, 12
	s_nop 0
	v_writelane_b32 v253, s1, 31
	s_add_i32 s0, s84, s15
	s_cmpk_lt_i32 s9, 0x1000
	v_writelane_b32 v253, s0, 32
	s_cselect_b64 s[0:1], -1, 0
	v_writelane_b32 v253, s0, 33
	s_cmpk_lt_i32 s9, 0x800
	s_nop 0
	v_writelane_b32 v253, s1, 34
	s_cselect_b64 s[0:1], -1, 0
	v_writelane_b32 v253, s0, 35
	s_cmpk_lt_i32 s86, 0x80
	s_nop 0
	v_writelane_b32 v253, s1, 36
	s_cselect_b64 s[0:1], -1, 0
	v_writelane_b32 v253, s0, 37
	s_nop 1
	v_writelane_b32 v253, s1, 38
	s_lshl_b32 s0, s88, 4
	s_cmpk_lg_i32 s85, 0x100
	v_writelane_b32 v253, s0, 39
	s_cselect_b64 s[2:3], -1, 0
	s_lshl_b32 s0, s86, 9
	s_cmpk_gt_u32 s86, 0x7f
	v_writelane_b32 v253, s0, 40
	s_cselect_b64 s[0:1], -1, 0
	s_or_b64 s[0:1], s[0:1], s[2:3]
	v_writelane_b32 v253, s0, 41
	s_lshl_b32 s72, s88, 10
	s_lshl_b32 s16, s88, 5
	v_writelane_b32 v253, s1, 42
	s_lshl_b32 s0, s88, 13
	s_add_i32 s41, s0, 0
	s_lshl_b32 s0, s90, 2
	s_add_i32 s0, s84, s0
	v_writelane_b32 v253, s0, 43
	s_add_i32 s0, s88, 8
	s_lshl_b32 s1, s0, 5
	v_writelane_b32 v253, s1, 44
	s_lshl_b32 s0, s0, 3
	v_writelane_b32 v253, s0, 45
	s_lshl_b32 s0, s85, 9
	v_writelane_b32 v253, s0, 46
	s_lshl_b32 s0, s88, 3
	s_cmp_lt_u32 s48, 64
	v_writelane_b32 v253, s0, 47
	s_cselect_b64 s[0:1], -1, 0
	v_writelane_b32 v253, s0, 48
	s_lshl_b32 s17, s88, 8
	s_nop 0
	v_writelane_b32 v253, s1, 49
	s_add_i32 s0, s84, s17
	s_cmpk_lt_i32 s9, 0x100
	v_writelane_b32 v253, s0, 50
	s_cselect_b64 s[0:1], -1, 0
	v_writelane_b32 v253, s0, 51
	s_add_i32 s7, s86, 0xffffff00
	s_add_i32 s18, s9, 0x4000
	v_writelane_b32 v253, s1, 52
	s_mul_i32 s0, s86, 7
	s_add_i32 s8, s7, s0
	s_cmpk_eq_i32 s85, 0x100
	s_cselect_b64 s[0:1], -1, 0
	v_writelane_b32 v253, s0, 53
	s_nop 1
	v_writelane_b32 v253, s1, 54
	s_and_b64 s[0:1], s[0:1], exec
	s_cselect_b32 s1, 64, s85
	s_cselect_b32 s10, s8, s49
	s_cselect_b32 s0, 0x700, s94
	s_cmp_ge_i32 s86, s1
	v_writelane_b32 v253, s0, 55
	s_cselect_b64 s[8:9], -1, 0
	v_writelane_b32 v253, s8, 56
	s_mul_i32 s0, s88, 0xffffe004
	s_add_i32 s14, s41, s0
	v_writelane_b32 v253, s9, 57
	s_lshl_b32 s0, s1, 9
	s_ashr_i32 s91, s90, 31
	v_writelane_b32 v253, s0, 58
	s_and_b32 s0, s16, 0x7fffff80
	s_cmpk_lt_i32 s86, 0x100
	s_cselect_b64 s[8:9], -1, 0
	v_writelane_b32 v253, s8, 59
	s_nop 1
	v_writelane_b32 v253, s9, 60
	s_and_b64 s[8:9], s[8:9], exec
	s_cselect_b32 s8, s86, 0
	s_ashr_i32 s9, s8, 31
	s_lshr_b32 s9, s9, 29
	s_add_i32 s9, s8, s9
	s_and_b32 s11, s9, -8
	s_sub_i32 s11, s8, s11
	s_ashr_i32 s8, s7, 31
	s_lshr_b32 s8, s8, 30
	s_waitcnt lgkmcnt(0)
	s_add_i32 s13, s7, s8
	s_and_b32 s8, s13, -4
	v_writelane_b32 v253, s8, 61
	s_sub_i32 s7, s7, s8
	s_ashr_i32 s12, s9, 3
	v_writelane_b32 v253, s7, 62
	s_lshl_b32 s7, s11, 5
	s_cmpk_lt_i32 s86, 0x110
	s_cselect_b64 s[8:9], -1, 0
	v_writelane_b32 v253, s8, 63
	s_cmpk_lt_i32 s86, 0x820
	s_nop 0
	v_writelane_b32 v254, s9, 0
	s_cselect_b64 s[8:9], -1, 0
	v_writelane_b32 v254, s8, 1
	s_cmp_gt_u32 s86, 31
	s_nop 0
	v_writelane_b32 v254, s9, 2
	s_cselect_b64 s[8:9], -1, 0
	s_or_b64 s[2:3], s[8:9], s[2:3]
	s_mul_i32 s8, s88, 0x3ffc
	s_add_i32 s9, s10, s88
	v_writelane_b32 v254, s14, 3
	s_add_i32 s8, s14, s8
	v_writelane_b32 v254, s8, 4
	s_cmpk_lt_i32 s9, 0x1f00
	v_writelane_b32 v254, s9, 5
	s_cselect_b64 s[8:9], -1, 0
	s_lshl_b32 s10, s13, 1
	s_and_b32 s10, s10, -8
	s_cmpk_lt_i32 s86, 0x120
	v_writelane_b32 v254, s10, 6
	s_cselect_b64 s[20:21], -1, 0
	v_writelane_b32 v254, s20, 7
	s_add_i32 s13, s72, 0
	s_bfe_u32 s10, s48, 0x30006
	v_writelane_b32 v254, s21, 8
	v_writelane_b32 v254, s13, 9
	s_add_i32 s13, s13, 0x13b80
	v_writelane_b32 v254, s13, 10
	s_cmp_lt_i32 s5, 2
	s_mul_i32 s13, s5, 0x52
	s_cselect_b32 s6, s13, s6
	s_add_i32 s6, s6, s4
	s_mul_hi_i32 s13, s6, 0x66666667
	s_lshr_b32 s14, s13, 31
	s_ashr_i32 s13, s13, 5
	s_add_i32 s13, s13, s14
	s_mul_i32 s14, s13, 0x50
	s_lshl_b32 s13, s13, 3
	s_sub_i32 s6, s6, s14
	s_sub_i32 s14, 0x41, s13
	s_min_u32 s14, s14, 8
	s_cmp_eq_u32 s10, 0
	s_cselect_b64 s[74:75], -1, 0
	s_cmp_lt_i32 s11, 0
	s_mul_i32 s11, s11, 33
	s_cselect_b32 s7, s11, s7
	s_add_i32 s7, s7, s12
	s_ashr_i32 s10, s7, 31
	s_lshr_b32 s10, s10, 27
	s_add_i32 s10, s7, s10
	s_and_b32 s11, s10, 0xffe0
	s_sub_i32 s7, s7, s11
	s_bfe_i32 s11, s7, 0x80000
	s_bfe_u32 s11, s11, 0x3000c
	s_add_i32 s11, s7, s11
	s_and_b32 s12, s11, 0xf8
	s_sub_i32 s7, s7, s12
	s_ashr_i32 s10, s10, 5
	s_lshl_b32 s10, s10, 3
	s_sext_i32_i8 s7, s7
	s_add_i32 s7, s10, s7
	v_writelane_b32 v254, s7, 11
	s_bfe_i32 s7, s11, 0x80000
	s_sext_i32_i16 s7, s7
	s_ashr_i32 s7, s7, 3
	v_writelane_b32 v254, s7, 12
	s_cmp_lt_i32 s5, 0
	s_movk_i32 s7, 0x100
	s_cselect_b32 s7, s7, 0x100
	s_and_b64 s[2:3], s[2:3], s[8:9]
	v_writelane_b32 v254, s2, 13
	v_cvt_f32_ubyte0_e32 v1, s14
	v_cvt_f32_i32_e32 v0, s6
	v_writelane_b32 v254, s3, 14
	s_mul_i32 s2, s5, s7
	s_add_i32 s2, s2, s4
	s_ashr_i32 s3, s2, 31
	s_lshr_b32 s3, s3, 24
	v_rcp_iflag_f32_e32 v2, v1
	s_add_i32 s3, s2, s3
	s_and_b32 s4, s3, 0xffffff00
	s_sub_i32 s7, s2, s4
	s_ashr_i32 s2, s3, 8
	s_lshl_b32 s8, s2, 3
	v_mul_f32_e32 v2, v0, v2
	s_sub_i32 s2, 0x41, s8
	v_trunc_f32_e32 v2, v2
	s_min_u32 s9, s2, 8
	s_ashr_i32 s2, s6, 30
	v_fma_f32 v0, -v2, v1, v0
	s_or_b32 s4, s2, 1
	v_cmp_ge_f32_e64 s[2:3], |v0|, v1
	v_cvt_i32_f32_e32 v0, v2
	s_and_b64 s[2:3], s[2:3], exec
	s_cselect_b32 s2, s4, 0
	v_cvt_f32_ubyte0_e32 v1, s9
	v_readfirstlane_b32 s3, v0
	s_add_i32 s2, s3, s2
	s_mul_i32 s3, s2, s14
	s_sub_i32 s3, s6, s3
	s_sext_i32_i8 s3, s3
	v_cvt_f32_i32_e32 v0, s7
	v_rcp_iflag_f32_e32 v2, v1
	s_bfe_i64 s[4:5], s[2:3], 0x80000
	s_lshl_b64 s[4:5], s[4:5], 19
	s_add_i32 s10, s13, s3
	v_writelane_b32 v254, s4, 15
	s_ashr_i32 s11, s10, 31
	v_mul_f32_e32 v2, v0, v2
	v_writelane_b32 v254, s5, 16
	s_mov_b32 s4, s10
	v_writelane_b32 v254, s4, 17
	v_trunc_f32_e32 v2, v2
	v_fma_f32 v0, -v2, v1, v0
	v_writelane_b32 v254, s5, 18
	s_lshl_b64 s[4:5], s[10:11], 19
	v_writelane_b32 v254, s4, 19
	s_ashr_i32 s3, s7, 30
	s_or_b32 s3, s3, 1
	v_writelane_b32 v254, s5, 20
	v_cmp_ge_f32_e64 s[4:5], |v0|, v1
	v_cvt_i32_f32_e32 v0, v2
	s_and_b64 s[4:5], s[4:5], exec
	s_sext_i32_i8 s2, s2
	v_writelane_b32 v254, s2, 21
	s_cselect_b32 s2, s3, 0
	v_readfirstlane_b32 s3, v0
	s_add_i32 s2, s3, s2
	s_mul_i32 s3, s2, s9
	s_sub_i32 s3, s7, s3
	s_sext_i32_i16 s3, s3
	s_add_i32 s3, s8, s3
	s_bitcmp1_b32 s86, 0
	v_writelane_b32 v254, s3, 22
	s_cselect_b64 s[4:5], -1, 0
	v_writelane_b32 v254, s4, 23
	s_bitcmp1_b32 s85, 0
	s_sext_i32_i16 s2, s2
	v_writelane_b32 v254, s5, 24
	s_cselect_b64 s[4:5], -1, 0
	v_writelane_b32 v254, s4, 25
	s_lshl_b32 s3, s86, 5
	s_lshl_b32 s0, s0, 1
	v_writelane_b32 v254, s5, 26
	s_lshl_b32 s4, s88, 2
	s_add_i32 s3, s3, s4
	v_writelane_b32 v254, s3, 27
	s_and_b32 s3, s86, 7
	s_lshl_b32 s3, s3, 2
	s_add_i32 s2, s2, s3
	s_and_b32 s2, s2, 31
	v_writelane_b32 v254, s2, 28
	s_add_i32 s2, s15, 0
	v_writelane_b32 v254, s15, 29
	s_add_i32 s3, s2, 0x10030
	v_writelane_b32 v254, s3, 30
	s_add_i32 s3, s2, 0x10130
	v_writelane_b32 v254, s3, 31
	s_add_i32 s3, s2, 0x10230
	v_writelane_b32 v254, s3, 32
	s_add_i32 s2, s2, 0x10330
	v_writelane_b32 v254, s2, 33
	s_mul_hi_i32 s3, s18, 0x2800
	s_mul_i32 s2, s18, 0x2800
	v_writelane_b32 v254, s2, 34
	s_ashr_i32 s19, s18, 31
	s_ashr_i32 s95, s94, 31
	v_writelane_b32 v254, s3, 35
	s_lshl_b32 s2, s1, 10
	v_writelane_b32 v254, s2, 36
	s_mulk_i32 s1, 0x600
	v_writelane_b32 v254, s1, 37
	s_lshl_b32 s1, s86, 11
	v_writelane_b32 v254, s17, 38
	s_add_i32 s1, s1, s17
	v_writelane_b32 v254, s1, 39
	s_lshl_b32 s1, s86, 8
	v_writelane_b32 v254, s16, 40
	s_add_i32 s1, s1, s16
	v_writelane_b32 v254, s1, 41
	v_writelane_b32 v254, s0, 42
	s_add_i32 s0, s90, 0xfffffe00
	v_writelane_b32 v254, s0, 43
	s_lshl_b32 s0, s85, 11
	v_writelane_b32 v254, s0, 44
	s_lshl_b32 s0, s85, 5
	v_writelane_b32 v254, s0, 45
	s_lshl_b32 s0, s85, 8
	v_writelane_b32 v254, s0, 46
	s_add_i32 s0, 0, 0x18800
	v_writelane_b32 v254, s0, 47
	s_add_i32 s0, 0, 0x19000
	v_writelane_b32 v254, s0, 48
	s_add_i32 s0, 0, 0x15b80
	v_writelane_b32 v254, s0, 49
	s_add_i32 s0, 0, 0x13010
	v_writelane_b32 v254, s0, 50
	s_add_i32 s0, 0, 0x13b40
	v_writelane_b32 v254, s0, 51
	s_add_i32 s0, 0, 0x13b44
	v_writelane_b32 v254, s0, 52
	s_add_i32 s0, 0, 0x20300
	v_writelane_b32 v254, s0, 53
	s_add_i32 s0, 0, 0xc840
	v_writelane_b32 v254, s0, 54
	s_mov_b32 s0, s18
	v_writelane_b32 v254, s0, 55
	v_writelane_b32 v255, s90, 1
	s_mov_b32 s2, s86
	v_writelane_b32 v254, s1, 56
	s_lshl_b64 s[0:1], s[18:19], 11
	v_writelane_b32 v254, s0, 57
	v_writelane_b32 v255, s91, 2
	v_writelane_b32 v255, s92, 3
	v_writelane_b32 v254, s1, 58
	s_mov_b64 s[0:1], 0
	v_writelane_b32 v254, s0, 59
	v_writelane_b32 v255, s93, 4
	s_lshl_b64 s[50:51], s[94:95], 11
	v_writelane_b32 v254, s1, 60
	v_writelane_b32 v254, s2, 61
	v_mbcnt_lo_u32_b32 v0, -1, 0
	v_mbcnt_hi_u32_b32 v180, -1, v0
	v_writelane_b32 v254, s3, 62
	s_mov_b32 s2, s94
	v_writelane_b32 v255, s2, 5
	s_mov_b64 s[0:1], 0x200000
	s_mov_b32 s4, s29
	v_writelane_b32 v255, s3, 6
	v_writelane_b32 v255, s87, 7
	v_writelane_b32 v255, s89, 8
	v_writelane_b32 v255, s96, 9
	v_writelane_b32 v254, s85, 63
	s_nop 0
	v_writelane_b32 v255, s97, 10
	v_writelane_b32 v255, s80, 11
	v_writelane_b32 v255, s82, 12
	s_nop 1
	v_writelane_b32 v255, s83, 13
	v_writelane_b32 v255, s81, 14
	v_writelane_b32 v255, s84, 15
	v_writelane_b32 v255, s72, 16
	v_writelane_b32 v255, s74, 17
	s_nop 1
	v_writelane_b32 v255, s75, 18
	v_writelane_b32 v255, s76, 19
	s_nop 1
	v_writelane_b32 v255, s77, 20
	v_writelane_b32 v255, s50, 21
	s_nop 1
	v_writelane_b32 v255, s51, 22
	s_branch .LBB0_334

.LBB0_1513:
	s_add_i32 s82, s82, 1
	s_mul_i32 s2, s82, s89
	s_mul_hi_u32 s3, s82, s85
	s_add_i32 s3, s3, s2
	s_mul_i32 s2, s82, s85
	s_add_u32 s4, s2, s86
	s_addc_u32 s5, s3, s87
	v_mov_b64_e32 v[0:1], 0x820
	v_cmp_lt_i64_e64 s[48:49], s[4:5], v[0:1]
	v_mov_b64_e32 v[0:1], 0x81f
	v_cmp_gt_i64_e32 vcc, s[4:5], v[0:1]
	s_cbranch_vccnz .LBB0_1515
	s_ashr_i32 s2, s4, 31
	s_lshr_b32 s2, s2, 29
	s_add_i32 s2, s4, s2
	s_ashr_i32 s3, s2, 3
	s_and_b32 s2, s2, -8
	s_sub_i32 s2, s4, s2
	s_lshl_b32 s4, s2, 2
	s_lshl_b32 s2, s2, 8
	s_add_i32 s4, s4, s3
	s_add_i32 s2, s2, s3
	s_addk_i32 s4, 0x700
	s_cmpk_lt_i32 s3, 0x100
	s_cselect_b32 s2, s2, s4
	s_ashr_i32 s3, s2, 31
	s_lshr_b32 s3, s3, 24
	s_add_i32 s3, s2, s3
	s_ashr_i32 s4, s3, 8
	s_lshl_b32 s4, s4, 3
	s_sub_i32 s5, 0x41, s4
	s_min_i32 s5, s5, 8
	s_abs_i32 s33, s5
	v_cvt_f32_u32_e32 v0, s33
	s_sub_i32 s38, 0, s33
	s_and_b32 s3, s3, 0xffffff00
	s_sub_i32 s2, s2, s3
	v_rcp_iflag_f32_e32 v0, v0
	s_abs_i32 s3, s2
	s_xor_b32 s37, s2, s5
	s_ashr_i32 s37, s37, 31
	v_mul_f32_e32 v0, 0x4f7ffffe, v0
	v_cvt_u32_f32_e32 v0, v0
	s_nop 0
	v_readfirstlane_b32 s39, v0
	s_mul_i32 s38, s38, s39
	s_mul_hi_u32 s38, s39, s38
	s_add_i32 s39, s39, s38
	s_mul_hi_u32 s38, s3, s39
	s_mul_i32 s39, s38, s33
	s_sub_i32 s3, s3, s39
	s_add_i32 s40, s38, 1
	s_sub_i32 s39, s3, s33
	s_cmp_ge_u32 s3, s33
	s_cselect_b32 s38, s40, s38
	s_cselect_b32 s3, s39, s3
	s_add_i32 s39, s38, 1
	s_cmp_ge_u32 s3, s33
	s_cselect_b32 s3, s39, s38
	s_xor_b32 s3, s3, s37
	s_sub_i32 s50, s3, s37
	s_mul_i32 s3, s50, s5
	s_sub_i32 s2, s2, s3
	s_add_i32 s44, s4, s2
	s_and_b32 s2, s86, 7
	s_lshl_b32 s2, s2, 2
	s_add_i32 s2, s50, s2
	s_and_b32 s2, s2, 31
	s_cmpk_lt_i32 s44, 64
	s_cselect_b32 s50, s2, s50
